# same early LDS-DMA issue (four pieces behind each of the first two fragment-read groups) in the gla_in (both), gla_res, mla_up and ffn_down K-loops as well as ffn_up
# speedup vs baseline: 1.0187x; 1.0046x over previous
; #define MFMA16(a, b, c) __builtin_amdgcn_mfma_f32_16x16x32_bf16((a), (b), (c), 0, 0, 0)
; #define RAW_BARRIER() do { asm volatile("s_waitcnt lgkmcnt(0)" ::: "memory"); __builtin_amdgcn_s_barrier(); } while (0)
; template <int AMODE, bool SWAPO = true>
; DI void mainloop_dma16(f32x4 (&acc)[4][2][2][2], const TD& c, const TD& n, bool hasn, bool primed, int& s, int tid) {
;     ...
;     for (int kt = 0; kt < nk; ++kt) {
;         asm volatile("s_waitcnt vmcnt(0)" ::: "memory");
;         RAW_BARRIER();
;         const int ns = s ^ 1, nkt = kt + 1;
;         const bool doload = nkt < nk;
;         const char* sb = smem + s * C::STAGE;
; #pragma unroll
;         for (int k2 = 0; k2 < 2; ++k2) {
;             const int co = ((4 * k2 + q) ^ key) << 4;
;             bf16x8 fw[2][2];
; #pragma unroll
;             for (int ni = 0; ni < 2; ++ni)
; #pragma unroll
;                 for (int rh = 0; rh < 2; ++rh) fw[ni][rh] = *(const bf16x8*)(sb + b_off + (ni * 32 + rh * 16) * 128 + co);
; #pragma unroll
;             for (int mh = 0; mh < 2; ++mh) {
;                 bf16x8 fx[2][2];
; #pragma unroll
;                 for (int m2 = 0; m2 < 2; ++m2)
; #pragma unroll
;                     for (int ch = 0; ch < 2; ++ch) fx[m2][ch] = *(const bf16x8*)(sb + a_off + ((2 * mh + m2) * 32 + ch * 16) * 128 + co);
;                 asm volatile("" ::: "memory");
;                 if (doload) { const int p0 = (2 * k2 + mh) * 2; piece(c, ao, bo, nkt, ns, p0); piece(c, ao, bo, nkt, ns, p0 + 1); }
;                 asm volatile("" ::: "memory");
; #pragma unroll
;                 for (int m2 = 0; m2 < 2; ++m2)
; #pragma unroll
;                     for (int ni = 0; ni < 2; ++ni)
; #pragma unroll
;                         for (int rh = 0; rh < 2; ++rh)
; #pragma unroll
;                             for (int ch = 0; ch < 2; ++ch)
;                                 acc[2 * mh + m2][ni][rh][ch] = SWAPO ? MFMA16(fw[ni][rh], fx[m2][ch], acc[2 * mh + m2][ni][rh][ch]) : MFMA16(fx[m2][ch], fw[ni][rh], acc[2 * mh + m2][ni][rh][ch]);
;             }
.LBB0_202:
	s_cmp_lt_u32 s55, 15
	s_cselect_b64 s[20:21], -1, 0
	s_lshl_b32 s0, s53, 16
	s_add_i32 s1, s0, 16
	v_add3_u32 v165, s1, v197, v195
	v_add3_u32 v163, s1, v196, v195
	s_waitcnt vmcnt(0)
	v_add_u32_e32 v128, v165, v205
	v_add_u32_e32 v167, v163, v205
	s_waitcnt lgkmcnt(0)
	s_barrier
	ds_read_b128 v[140:143], v128 offset:32768
	ds_read_b128 v[136:139], v128 offset:34816
	ds_read_b128 v[132:135], v128 offset:36864
	ds_read_b128 v[128:131], v128 offset:38912
	ds_read_b128 v[152:155], v167
	ds_read_b128 v[156:159], v167 offset:2048
	ds_read_b128 v[144:147], v167 offset:4096
	ds_read_b128 v[148:151], v167 offset:6144
	s_xor_b32 s0, s0, 0x10000
	s_cmp_gt_u32 s55, 14
	v_add_u32_e32 v161, s0, v204
	s_cbranch_scc1 .LBB0_204
	v_lshl_add_u64 v[208:209], v[178:179], 0, s[40:41]
	v_readfirstlane_b32 s0, v161
	s_mov_b32 m0, s0
	s_nop 0
	global_load_lds_dwordx4 v[208:209], off
	v_add_u32_e32 v214, 0x400, v161
	v_lshl_add_u64 v[208:209], v[180:181], 0, s[40:41]
	v_readfirstlane_b32 s0, v214
	s_mov_b32 m0, s0
	s_nop 0
	global_load_lds_dwordx4 v[208:209], off
	v_add_u32_e32 v214, 0x800, v161
	v_lshl_add_u64 v[208:209], v[182:183], 0, s[40:41]
	v_readfirstlane_b32 s0, v214
	s_mov_b32 m0, s0
	s_nop 0
	global_load_lds_dwordx4 v[208:209], off
	v_add_u32_e32 v214, 0xc00, v161
	v_lshl_add_u64 v[208:209], v[184:185], 0, s[40:41]
	v_readfirstlane_b32 s0, v214
	s_mov_b32 m0, s0
	s_nop 0
	global_load_lds_dwordx4 v[208:209], off
.LBB0_204:
	s_waitcnt lgkmcnt(0)
	v_mfma_f32_16x16x32_bf16 v[124:127], v[140:143], v[152:155], v[124:127]
	s_andn2_b64 vcc, exec, s[20:21]
	v_mfma_f32_16x16x32_bf16 v[116:119], v[140:143], v[156:159], v[116:119]
	v_mfma_f32_16x16x32_bf16 v[120:123], v[136:139], v[152:155], v[120:123]
	v_mfma_f32_16x16x32_bf16 v[108:111], v[136:139], v[156:159], v[108:111]
	v_mfma_f32_16x16x32_bf16 v[112:115], v[132:135], v[152:155], v[112:115]
	v_mfma_f32_16x16x32_bf16 v[100:103], v[132:135], v[156:159], v[100:103]
	v_mfma_f32_16x16x32_bf16 v[104:107], v[128:131], v[152:155], v[104:107]
	v_mfma_f32_16x16x32_bf16 v[96:99], v[128:131], v[156:159], v[96:99]
	v_mfma_f32_16x16x32_bf16 v[92:95], v[140:143], v[144:147], v[92:95]
	v_mfma_f32_16x16x32_bf16 v[84:87], v[140:143], v[148:151], v[84:87]
	v_mfma_f32_16x16x32_bf16 v[88:91], v[136:139], v[144:147], v[88:91]
	v_mfma_f32_16x16x32_bf16 v[76:79], v[136:139], v[148:151], v[76:79]
	v_mfma_f32_16x16x32_bf16 v[80:83], v[132:135], v[144:147], v[80:83]
	v_mfma_f32_16x16x32_bf16 v[68:71], v[132:135], v[148:151], v[68:71]
	v_mfma_f32_16x16x32_bf16 v[72:75], v[128:131], v[144:147], v[72:75]
	v_mfma_f32_16x16x32_bf16 v[64:67], v[128:131], v[148:151], v[64:67]
	ds_read_b128 v[152:155], v167 offset:8192
	ds_read_b128 v[156:159], v167 offset:10240
	ds_read_b128 v[144:147], v167 offset:12288
	ds_read_b128 v[148:151], v167 offset:14336
	v_cndmask_b32_e64 v167, 0, 1, s[20:21]
	v_cmp_ne_u32_e64 s[0:1], 1, v167
	s_cbranch_vccnz .LBB0_206
	v_add_u32_e32 v214, 0x8000, v161
	v_lshl_add_u64 v[208:209], v[186:187], 0, s[40:41]
	v_readfirstlane_b32 s20, v214
	s_mov_b32 m0, s20
	s_nop 0
	global_load_lds_dwordx4 v[208:209], off
	v_add_u32_e32 v214, 0x8400, v161
	v_lshl_add_u64 v[208:209], v[188:189], 0, s[40:41]
	v_readfirstlane_b32 s20, v214
	s_mov_b32 m0, s20
	s_nop 0
	global_load_lds_dwordx4 v[208:209], off
	v_add_u32_e32 v214, 0x8800, v161
	v_lshl_add_u64 v[208:209], v[190:191], 0, s[40:41]
	v_readfirstlane_b32 s20, v214
	s_mov_b32 m0, s20
	s_nop 0
	global_load_lds_dwordx4 v[208:209], off
	v_add_u32_e32 v214, 0x8c00, v161
	v_lshl_add_u64 v[208:209], v[192:193], 0, s[40:41]
	v_readfirstlane_b32 s20, v214
	s_mov_b32 m0, s20
	s_nop 0
	global_load_lds_dwordx4 v[208:209], off

; #define MFMA16(a, b, c) __builtin_amdgcn_mfma_f32_16x16x32_bf16((a), (b), (c), 0, 0, 0)
; template <int AMODE, bool SWAPO = true>
; DI void mainloop_dma16(f32x4 (&acc)[4][2][2][2], const TD& c, const TD& n, bool hasn, bool primed, int& s, int tid) {
;     ...
; #pragma unroll
;         for (int k2 = 0; k2 < 2; ++k2) {
;             const int co = ((4 * k2 + q) ^ key) << 4;
;             bf16x8 fw[2][2];
; #pragma unroll
;             for (int ni = 0; ni < 2; ++ni)
; #pragma unroll
;                 for (int rh = 0; rh < 2; ++rh) fw[ni][rh] = *(const bf16x8*)(sb + b_off + (ni * 32 + rh * 16) * 128 + co);
; #pragma unroll
;             for (int mh = 0; mh < 2; ++mh) {
;                 bf16x8 fx[2][2];
; #pragma unroll
;                 for (int m2 = 0; m2 < 2; ++m2)
; #pragma unroll
;                     for (int ch = 0; ch < 2; ++ch) fx[m2][ch] = *(const bf16x8*)(sb + a_off + ((2 * mh + m2) * 32 + ch * 16) * 128 + co);
;                 asm volatile("" ::: "memory");
;                 if (doload) { const int p0 = (2 * k2 + mh) * 2; piece(c, ao, bo, nkt, ns, p0); piece(c, ao, bo, nkt, ns, p0 + 1); }
;                 asm volatile("" ::: "memory");
; #pragma unroll
;                 for (int m2 = 0; m2 < 2; ++m2)
; #pragma unroll
;                     for (int ni = 0; ni < 2; ++ni)
; #pragma unroll
;                         for (int rh = 0; rh < 2; ++rh)
; #pragma unroll
;                             for (int ch = 0; ch < 2; ++ch)
;                                 acc[2 * mh + m2][ni][rh][ch] = SWAPO ? MFMA16(fw[ni][rh], fx[m2][ch], acc[2 * mh + m2][ni][rh][ch]) : MFMA16(fx[m2][ch], fw[ni][rh], acc[2 * mh + m2][ni][rh][ch]);
;             }
.LBB0_208:
	s_waitcnt lgkmcnt(0)
	v_mfma_f32_16x16x32_bf16 v[124:127], v[140:143], v[152:155], v[124:127]
	s_and_b64 vcc, exec, s[0:1]
	v_mfma_f32_16x16x32_bf16 v[116:119], v[140:143], v[156:159], v[116:119]
	v_mfma_f32_16x16x32_bf16 v[120:123], v[144:147], v[152:155], v[120:123]
	v_mfma_f32_16x16x32_bf16 v[108:111], v[144:147], v[156:159], v[108:111]
	v_mfma_f32_16x16x32_bf16 v[112:115], v[136:139], v[152:155], v[112:115]
	v_mfma_f32_16x16x32_bf16 v[100:103], v[136:139], v[156:159], v[100:103]
	v_mfma_f32_16x16x32_bf16 v[104:107], v[128:131], v[152:155], v[104:107]
	v_mfma_f32_16x16x32_bf16 v[96:99], v[128:131], v[156:159], v[96:99]
	v_mfma_f32_16x16x32_bf16 v[92:95], v[140:143], v[132:135], v[92:95]
	v_mfma_f32_16x16x32_bf16 v[84:87], v[140:143], v[148:151], v[84:87]
	v_mfma_f32_16x16x32_bf16 v[88:91], v[144:147], v[132:135], v[88:91]
	v_mfma_f32_16x16x32_bf16 v[76:79], v[144:147], v[148:151], v[76:79]
	v_mfma_f32_16x16x32_bf16 v[80:83], v[136:139], v[132:135], v[80:83]
	v_mfma_f32_16x16x32_bf16 v[68:71], v[136:139], v[148:151], v[68:71]
	v_mfma_f32_16x16x32_bf16 v[72:75], v[128:131], v[132:135], v[72:75]
	v_mfma_f32_16x16x32_bf16 v[64:67], v[128:131], v[148:151], v[64:67]
	ds_read_b128 v[152:155], v163 offset:8192
	ds_read_b128 v[156:159], v163 offset:10240
	ds_read_b128 v[148:151], v163 offset:12288
	ds_read_b128 v[132:135], v163 offset:14336
	s_cbranch_vccnz .LBB0_201
	s_branch .LBB0_201

; #define MFMA16(a, b, c) __builtin_amdgcn_mfma_f32_16x16x32_bf16((a), (b), (c), 0, 0, 0)
; #define RAW_BARRIER() do { asm volatile("s_waitcnt lgkmcnt(0)" ::: "memory"); __builtin_amdgcn_s_barrier(); } while (0)
; template <int AMODE, bool SWAPO = true>
; DI void mainloop_dma16(f32x4 (&acc)[4][2][2][2], const TD& c, const TD& n, bool hasn, bool primed, int& s, int tid) {
;     ...
;     for (int kt = 0; kt < nk; ++kt) {
;         asm volatile("s_waitcnt vmcnt(0)" ::: "memory");
;         RAW_BARRIER();
;         const int ns = s ^ 1, nkt = kt + 1;
;         const bool doload = nkt < nk;
;         const char* sb = smem + s * C::STAGE;
; #pragma unroll
;         for (int k2 = 0; k2 < 2; ++k2) {
;             const int co = ((4 * k2 + q) ^ key) << 4;
;             bf16x8 fw[2][2];
; #pragma unroll
;             for (int ni = 0; ni < 2; ++ni)
; #pragma unroll
;                 for (int rh = 0; rh < 2; ++rh) fw[ni][rh] = *(const bf16x8*)(sb + b_off + (ni * 32 + rh * 16) * 128 + co);
; #pragma unroll
;             for (int mh = 0; mh < 2; ++mh) {
;                 bf16x8 fx[2][2];
; #pragma unroll
;                 for (int m2 = 0; m2 < 2; ++m2)
; #pragma unroll
;                     for (int ch = 0; ch < 2; ++ch) fx[m2][ch] = *(const bf16x8*)(sb + a_off + ((2 * mh + m2) * 32 + ch * 16) * 128 + co);
;                 asm volatile("" ::: "memory");
;                 if (doload) { const int p0 = (2 * k2 + mh) * 2; piece(c, ao, bo, nkt, ns, p0); piece(c, ao, bo, nkt, ns, p0 + 1); }
;                 asm volatile("" ::: "memory");
; #pragma unroll
;                 for (int m2 = 0; m2 < 2; ++m2)
; #pragma unroll
;                     for (int ni = 0; ni < 2; ++ni)
; #pragma unroll
;                         for (int rh = 0; rh < 2; ++rh)
; #pragma unroll
;                             for (int ch = 0; ch < 2; ++ch)
;                                 acc[2 * mh + m2][ni][rh][ch] = SWAPO ? MFMA16(fw[ni][rh], fx[m2][ch], acc[2 * mh + m2][ni][rh][ch]) : MFMA16(fx[m2][ch], fw[ni][rh], acc[2 * mh + m2][ni][rh][ch]);
;             }
.LBB0_336:
	s_cmp_lt_u32 s40, 15
	s_cselect_b64 s[20:21], -1, 0
	s_lshl_b32 s0, s53, 16
	s_add_i32 s1, s0, 16
	v_add3_u32 v179, s1, v197, v195
	v_add3_u32 v178, s1, v196, v195
	s_waitcnt vmcnt(0)
	v_add_u32_e32 v128, v179, v205
	v_add_u32_e32 v180, v178, v205
	s_waitcnt lgkmcnt(0)
	s_barrier
	ds_read_b128 v[140:143], v128 offset:32768
	ds_read_b128 v[136:139], v128 offset:34816
	ds_read_b128 v[132:135], v128 offset:36864
	ds_read_b128 v[128:131], v128 offset:38912
	ds_read_b128 v[152:155], v180
	ds_read_b128 v[156:159], v180 offset:2048
	ds_read_b128 v[144:147], v180 offset:4096
	ds_read_b128 v[148:151], v180 offset:6144
	s_xor_b32 s0, s0, 0x10000
	s_cmp_gt_u32 s40, 14
	v_add_u32_e32 v176, s0, v204
	s_cbranch_scc1 .LBB0_338
	v_lshl_add_u64 v[182:183], v[174:175], 0, s[34:35]
	v_readfirstlane_b32 s0, v176
	s_mov_b32 m0, s0
	s_nop 0
	global_load_lds_dwordx4 v[182:183], off
	v_add_u32_e32 v184, 0x400, v176
	v_lshl_add_u64 v[182:183], v[172:173], 0, s[34:35]
	v_readfirstlane_b32 s0, v184
	s_mov_b32 m0, s0
	s_nop 0
	global_load_lds_dwordx4 v[182:183], off
	v_add_u32_e32 v184, 0x800, v176
	v_lshl_add_u64 v[182:183], v[170:171], 0, s[34:35]
	v_readfirstlane_b32 s0, v184
	s_mov_b32 m0, s0
	s_nop 0
	global_load_lds_dwordx4 v[182:183], off
	v_add_u32_e32 v184, 0xc00, v176
	v_lshl_add_u64 v[182:183], v[168:169], 0, s[34:35]
	v_readfirstlane_b32 s0, v184
	s_mov_b32 m0, s0
	s_nop 0
	global_load_lds_dwordx4 v[182:183], off
.LBB0_338:
	s_waitcnt lgkmcnt(0)
	v_mfma_f32_16x16x32_bf16 v[124:127], v[152:155], v[140:143], v[124:127]
	s_andn2_b64 vcc, exec, s[20:21]
	v_mfma_f32_16x16x32_bf16 v[116:119], v[156:159], v[140:143], v[116:119]
	v_mfma_f32_16x16x32_bf16 v[120:123], v[152:155], v[136:139], v[120:123]
	v_mfma_f32_16x16x32_bf16 v[108:111], v[156:159], v[136:139], v[108:111]
	v_mfma_f32_16x16x32_bf16 v[112:115], v[152:155], v[132:135], v[112:115]
	v_mfma_f32_16x16x32_bf16 v[100:103], v[156:159], v[132:135], v[100:103]
	v_mfma_f32_16x16x32_bf16 v[104:107], v[152:155], v[128:131], v[104:107]
	v_mfma_f32_16x16x32_bf16 v[96:99], v[156:159], v[128:131], v[96:99]
	v_mfma_f32_16x16x32_bf16 v[92:95], v[144:147], v[140:143], v[92:95]
	v_mfma_f32_16x16x32_bf16 v[84:87], v[148:151], v[140:143], v[84:87]
	v_mfma_f32_16x16x32_bf16 v[88:91], v[144:147], v[136:139], v[88:91]
	v_mfma_f32_16x16x32_bf16 v[76:79], v[148:151], v[136:139], v[76:79]
	v_mfma_f32_16x16x32_bf16 v[80:83], v[144:147], v[132:135], v[80:83]
	v_mfma_f32_16x16x32_bf16 v[68:71], v[148:151], v[132:135], v[68:71]
	v_mfma_f32_16x16x32_bf16 v[72:75], v[144:147], v[128:131], v[72:75]
	v_mfma_f32_16x16x32_bf16 v[64:67], v[148:151], v[128:131], v[64:67]
	ds_read_b128 v[152:155], v180 offset:8192
	ds_read_b128 v[156:159], v180 offset:10240
	ds_read_b128 v[144:147], v180 offset:12288
	ds_read_b128 v[148:151], v180 offset:14336
	v_cndmask_b32_e64 v180, 0, 1, s[20:21]
	v_cmp_ne_u32_e64 s[0:1], 1, v180
	s_cbranch_vccnz .LBB0_340
	v_add_u32_e32 v182, 0x8000, v176
	v_lshl_add_u64 v[180:181], v[160:161], 0, s[34:35]
	v_readfirstlane_b32 s20, v182
	s_mov_b32 m0, s20
	s_nop 0
	global_load_lds_dwordx4 v[180:181], off
	v_add_u32_e32 v182, 0x8400, v176
	v_lshl_add_u64 v[180:181], v[162:163], 0, s[34:35]
	v_readfirstlane_b32 s20, v182
	s_mov_b32 m0, s20
	s_nop 0
	global_load_lds_dwordx4 v[180:181], off
	v_add_u32_e32 v182, 0x8800, v176
	v_lshl_add_u64 v[180:181], v[164:165], 0, s[34:35]
	v_readfirstlane_b32 s20, v182
	s_mov_b32 m0, s20
	s_nop 0
	global_load_lds_dwordx4 v[180:181], off
	v_add_u32_e32 v182, 0x8c00, v176
	v_lshl_add_u64 v[180:181], v[166:167], 0, s[34:35]
	v_readfirstlane_b32 s20, v182
	s_mov_b32 m0, s20
	s_nop 0
	global_load_lds_dwordx4 v[180:181], off

; #define MFMA16(a, b, c) __builtin_amdgcn_mfma_f32_16x16x32_bf16((a), (b), (c), 0, 0, 0)
; template <int AMODE, bool SWAPO = true>
; DI void mainloop_dma16(f32x4 (&acc)[4][2][2][2], const TD& c, const TD& n, bool hasn, bool primed, int& s, int tid) {
;     ...
; #pragma unroll
;         for (int k2 = 0; k2 < 2; ++k2) {
;             const int co = ((4 * k2 + q) ^ key) << 4;
;             bf16x8 fw[2][2];
; #pragma unroll
;             for (int ni = 0; ni < 2; ++ni)
; #pragma unroll
;                 for (int rh = 0; rh < 2; ++rh) fw[ni][rh] = *(const bf16x8*)(sb + b_off + (ni * 32 + rh * 16) * 128 + co);
; #pragma unroll
;             for (int mh = 0; mh < 2; ++mh) {
;                 bf16x8 fx[2][2];
; #pragma unroll
;                 for (int m2 = 0; m2 < 2; ++m2)
; #pragma unroll
;                     for (int ch = 0; ch < 2; ++ch) fx[m2][ch] = *(const bf16x8*)(sb + a_off + ((2 * mh + m2) * 32 + ch * 16) * 128 + co);
;                 asm volatile("" ::: "memory");
;                 if (doload) { const int p0 = (2 * k2 + mh) * 2; piece(c, ao, bo, nkt, ns, p0); piece(c, ao, bo, nkt, ns, p0 + 1); }
;                 asm volatile("" ::: "memory");
; #pragma unroll
;                 for (int m2 = 0; m2 < 2; ++m2)
; #pragma unroll
;                     for (int ni = 0; ni < 2; ++ni)
; #pragma unroll
;                         for (int rh = 0; rh < 2; ++rh)
; #pragma unroll
;                             for (int ch = 0; ch < 2; ++ch)
;                                 acc[2 * mh + m2][ni][rh][ch] = SWAPO ? MFMA16(fw[ni][rh], fx[m2][ch], acc[2 * mh + m2][ni][rh][ch]) : MFMA16(fx[m2][ch], fw[ni][rh], acc[2 * mh + m2][ni][rh][ch]);
;             }
.LBB0_342:
	s_waitcnt lgkmcnt(0)
	v_mfma_f32_16x16x32_bf16 v[124:127], v[152:155], v[140:143], v[124:127]
	s_and_b64 vcc, exec, s[0:1]
	v_mfma_f32_16x16x32_bf16 v[116:119], v[156:159], v[140:143], v[116:119]
	v_mfma_f32_16x16x32_bf16 v[120:123], v[152:155], v[144:147], v[120:123]
	v_mfma_f32_16x16x32_bf16 v[108:111], v[156:159], v[144:147], v[108:111]
	v_mfma_f32_16x16x32_bf16 v[112:115], v[152:155], v[136:139], v[112:115]
	v_mfma_f32_16x16x32_bf16 v[100:103], v[156:159], v[136:139], v[100:103]
	v_mfma_f32_16x16x32_bf16 v[104:107], v[152:155], v[128:131], v[104:107]
	v_mfma_f32_16x16x32_bf16 v[96:99], v[156:159], v[128:131], v[96:99]
	v_mfma_f32_16x16x32_bf16 v[92:95], v[132:135], v[140:143], v[92:95]
	v_mfma_f32_16x16x32_bf16 v[84:87], v[148:151], v[140:143], v[84:87]
	v_mfma_f32_16x16x32_bf16 v[88:91], v[132:135], v[144:147], v[88:91]
	v_mfma_f32_16x16x32_bf16 v[76:79], v[148:151], v[144:147], v[76:79]
	v_mfma_f32_16x16x32_bf16 v[80:83], v[132:135], v[136:139], v[80:83]
	v_mfma_f32_16x16x32_bf16 v[68:71], v[148:151], v[136:139], v[68:71]
	v_mfma_f32_16x16x32_bf16 v[72:75], v[132:135], v[128:131], v[72:75]
	v_mfma_f32_16x16x32_bf16 v[64:67], v[148:151], v[128:131], v[64:67]
	ds_read_b128 v[152:155], v178 offset:8192
	ds_read_b128 v[156:159], v178 offset:10240
	ds_read_b128 v[148:151], v178 offset:12288
	ds_read_b128 v[132:135], v178 offset:14336
	s_cbranch_vccnz .LBB0_335
	s_branch .LBB0_335

; #define MFMA16(a, b, c) __builtin_amdgcn_mfma_f32_16x16x32_bf16((a), (b), (c), 0, 0, 0)
; #define RAW_BARRIER() do { asm volatile("s_waitcnt lgkmcnt(0)" ::: "memory"); __builtin_amdgcn_s_barrier(); } while (0)
; template <int AMODE, bool SWAPO = true>
; DI void mainloop_dma16(f32x4 (&acc)[4][2][2][2], const TD& c, const TD& n, bool hasn, bool primed, int& s, int tid) {
;     ...
;     for (int kt = 0; kt < nk; ++kt) {
;         asm volatile("s_waitcnt vmcnt(0)" ::: "memory");
;         RAW_BARRIER();
;         const int ns = s ^ 1, nkt = kt + 1;
;         const bool doload = nkt < nk;
;         const char* sb = smem + s * C::STAGE;
; #pragma unroll
;         for (int k2 = 0; k2 < 2; ++k2) {
;             const int co = ((4 * k2 + q) ^ key) << 4;
;             bf16x8 fw[2][2];
; #pragma unroll
;             for (int ni = 0; ni < 2; ++ni)
; #pragma unroll
;                 for (int rh = 0; rh < 2; ++rh) fw[ni][rh] = *(const bf16x8*)(sb + b_off + (ni * 32 + rh * 16) * 128 + co);
; #pragma unroll
;             for (int mh = 0; mh < 2; ++mh) {
;                 bf16x8 fx[2][2];
; #pragma unroll
;                 for (int m2 = 0; m2 < 2; ++m2)
; #pragma unroll
;                     for (int ch = 0; ch < 2; ++ch) fx[m2][ch] = *(const bf16x8*)(sb + a_off + ((2 * mh + m2) * 32 + ch * 16) * 128 + co);
;                 asm volatile("" ::: "memory");
;                 if (doload) { const int p0 = (2 * k2 + mh) * 2; piece(c, ao, bo, nkt, ns, p0); piece(c, ao, bo, nkt, ns, p0 + 1); }
;                 asm volatile("" ::: "memory");
; #pragma unroll
;                 for (int m2 = 0; m2 < 2; ++m2)
; #pragma unroll
;                     for (int ni = 0; ni < 2; ++ni)
; #pragma unroll
;                         for (int rh = 0; rh < 2; ++rh)
; #pragma unroll
;                             for (int ch = 0; ch < 2; ++ch)
;                                 acc[2 * mh + m2][ni][rh][ch] = SWAPO ? MFMA16(fw[ni][rh], fx[m2][ch], acc[2 * mh + m2][ni][rh][ch]) : MFMA16(fx[m2][ch], fw[ni][rh], acc[2 * mh + m2][ni][rh][ch]);
;             }
.LBB0_581:
	s_cmp_lt_u32 s41, 15
	s_cselect_b64 s[20:21], -1, 0
	s_lshl_b32 s0, s28, 16
	s_add_i32 s1, s0, 16
	v_add3_u32 v192, s1, v181, v179
	v_add3_u32 v191, s1, v180, v179
	s_waitcnt vmcnt(0)
	v_add_u32_e32 v128, v192, v189
	v_add_u32_e32 v193, v191, v189
	s_waitcnt lgkmcnt(0)
	s_barrier
	ds_read_b128 v[140:143], v128 offset:32768
	ds_read_b128 v[136:139], v128 offset:34816
	ds_read_b128 v[132:135], v128 offset:36864
	ds_read_b128 v[128:131], v128 offset:38912
	ds_read_b128 v[152:155], v193
	ds_read_b128 v[156:159], v193 offset:2048
	ds_read_b128 v[144:147], v193 offset:4096
	ds_read_b128 v[148:151], v193 offset:6144
	s_xor_b32 s0, s0, 0x10000
	s_cmp_gt_u32 s41, 14
	v_add_u32_e32 v176, s0, v188
	s_cbranch_scc1 .LBB0_583
	v_lshl_add_u64 v[194:195], v[160:161], 0, s[26:27]
	v_readfirstlane_b32 s0, v176
	s_mov_b32 m0, s0
	s_nop 0
	global_load_lds_dwordx4 v[194:195], off
	v_add_u32_e32 v196, 0x400, v176
	v_lshl_add_u64 v[194:195], v[162:163], 0, s[26:27]
	v_readfirstlane_b32 s0, v196
	s_mov_b32 m0, s0
	s_nop 0
	global_load_lds_dwordx4 v[194:195], off
	v_add_u32_e32 v196, 0x800, v176
	v_lshl_add_u64 v[194:195], v[164:165], 0, s[26:27]
	v_readfirstlane_b32 s0, v196
	s_mov_b32 m0, s0
	s_nop 0
	global_load_lds_dwordx4 v[194:195], off
	v_add_u32_e32 v196, 0xc00, v176
	v_lshl_add_u64 v[194:195], v[166:167], 0, s[26:27]
	v_readfirstlane_b32 s0, v196
	s_mov_b32 m0, s0
	s_nop 0
	global_load_lds_dwordx4 v[194:195], off
.LBB0_583:
	s_waitcnt lgkmcnt(0)
	v_mfma_f32_16x16x32_bf16 v[124:127], v[140:143], v[152:155], v[124:127]
	s_andn2_b64 vcc, exec, s[20:21]
	v_mfma_f32_16x16x32_bf16 v[108:111], v[140:143], v[156:159], v[108:111]
	v_mfma_f32_16x16x32_bf16 v[120:123], v[136:139], v[152:155], v[120:123]
	v_mfma_f32_16x16x32_bf16 v[104:107], v[136:139], v[156:159], v[104:107]
	v_mfma_f32_16x16x32_bf16 v[116:119], v[132:135], v[152:155], v[116:119]
	v_mfma_f32_16x16x32_bf16 v[100:103], v[132:135], v[156:159], v[100:103]
	v_mfma_f32_16x16x32_bf16 v[112:115], v[128:131], v[152:155], v[112:115]
	v_mfma_f32_16x16x32_bf16 v[96:99], v[128:131], v[156:159], v[96:99]
	v_mfma_f32_16x16x32_bf16 v[92:95], v[140:143], v[144:147], v[92:95]
	v_mfma_f32_16x16x32_bf16 v[76:79], v[140:143], v[148:151], v[76:79]
	v_mfma_f32_16x16x32_bf16 v[88:91], v[136:139], v[144:147], v[88:91]
	v_mfma_f32_16x16x32_bf16 v[72:75], v[136:139], v[148:151], v[72:75]
	v_mfma_f32_16x16x32_bf16 v[84:87], v[132:135], v[144:147], v[84:87]
	v_mfma_f32_16x16x32_bf16 v[68:71], v[132:135], v[148:151], v[68:71]
	v_mfma_f32_16x16x32_bf16 v[80:83], v[128:131], v[144:147], v[80:83]
	v_mfma_f32_16x16x32_bf16 v[64:67], v[128:131], v[148:151], v[64:67]
	ds_read_b128 v[152:155], v193 offset:8192
	ds_read_b128 v[156:159], v193 offset:10240
	ds_read_b128 v[144:147], v193 offset:12288
	ds_read_b128 v[148:151], v193 offset:14336
	v_cndmask_b32_e64 v193, 0, 1, s[20:21]
	v_cmp_ne_u32_e64 s[0:1], 1, v193
	s_cbranch_vccnz .LBB0_585
	v_add_u32_e32 v196, 0x8000, v176
	v_lshl_add_u64 v[194:195], v[168:169], 0, s[26:27]
	v_readfirstlane_b32 s20, v196
	s_mov_b32 m0, s20
	s_nop 0
	global_load_lds_dwordx4 v[194:195], off
	v_add_u32_e32 v196, 0x8400, v176
	v_lshl_add_u64 v[194:195], v[170:171], 0, s[26:27]
	v_readfirstlane_b32 s20, v196
	s_mov_b32 m0, s20
	s_nop 0
	global_load_lds_dwordx4 v[194:195], off
	v_add_u32_e32 v196, 0x8800, v176
	v_lshl_add_u64 v[194:195], v[172:173], 0, s[26:27]
	v_readfirstlane_b32 s20, v196
	s_mov_b32 m0, s20
	s_nop 0
	global_load_lds_dwordx4 v[194:195], off
	v_add_u32_e32 v196, 0x8c00, v176
	v_lshl_add_u64 v[194:195], v[174:175], 0, s[26:27]
	v_readfirstlane_b32 s20, v196
	s_mov_b32 m0, s20
	s_nop 0
	global_load_lds_dwordx4 v[194:195], off

; #define MFMA16(a, b, c) __builtin_amdgcn_mfma_f32_16x16x32_bf16((a), (b), (c), 0, 0, 0)
; template <int AMODE, bool SWAPO = true>
; DI void mainloop_dma16(f32x4 (&acc)[4][2][2][2], const TD& c, const TD& n, bool hasn, bool primed, int& s, int tid) {
;     ...
; #pragma unroll
;         for (int k2 = 0; k2 < 2; ++k2) {
;             const int co = ((4 * k2 + q) ^ key) << 4;
;             bf16x8 fw[2][2];
; #pragma unroll
;             for (int ni = 0; ni < 2; ++ni)
; #pragma unroll
;                 for (int rh = 0; rh < 2; ++rh) fw[ni][rh] = *(const bf16x8*)(sb + b_off + (ni * 32 + rh * 16) * 128 + co);
; #pragma unroll
;             for (int mh = 0; mh < 2; ++mh) {
;                 bf16x8 fx[2][2];
; #pragma unroll
;                 for (int m2 = 0; m2 < 2; ++m2)
; #pragma unroll
;                     for (int ch = 0; ch < 2; ++ch) fx[m2][ch] = *(const bf16x8*)(sb + a_off + ((2 * mh + m2) * 32 + ch * 16) * 128 + co);
;                 asm volatile("" ::: "memory");
;                 if (doload) { const int p0 = (2 * k2 + mh) * 2; piece(c, ao, bo, nkt, ns, p0); piece(c, ao, bo, nkt, ns, p0 + 1); }
;                 asm volatile("" ::: "memory");
; #pragma unroll
;                 for (int m2 = 0; m2 < 2; ++m2)
; #pragma unroll
;                     for (int ni = 0; ni < 2; ++ni)
; #pragma unroll
;                         for (int rh = 0; rh < 2; ++rh)
; #pragma unroll
;                             for (int ch = 0; ch < 2; ++ch)
;                                 acc[2 * mh + m2][ni][rh][ch] = SWAPO ? MFMA16(fw[ni][rh], fx[m2][ch], acc[2 * mh + m2][ni][rh][ch]) : MFMA16(fx[m2][ch], fw[ni][rh], acc[2 * mh + m2][ni][rh][ch]);
;             }
.LBB0_587:
	s_waitcnt lgkmcnt(0)
	v_mfma_f32_16x16x32_bf16 v[124:127], v[140:143], v[152:155], v[124:127]
	s_and_b64 vcc, exec, s[0:1]
	v_mfma_f32_16x16x32_bf16 v[108:111], v[140:143], v[156:159], v[108:111]
	v_mfma_f32_16x16x32_bf16 v[120:123], v[144:147], v[152:155], v[120:123]
	v_mfma_f32_16x16x32_bf16 v[104:107], v[144:147], v[156:159], v[104:107]
	v_mfma_f32_16x16x32_bf16 v[116:119], v[136:139], v[152:155], v[116:119]
	v_mfma_f32_16x16x32_bf16 v[100:103], v[136:139], v[156:159], v[100:103]
	v_mfma_f32_16x16x32_bf16 v[112:115], v[128:131], v[152:155], v[112:115]
	v_mfma_f32_16x16x32_bf16 v[96:99], v[128:131], v[156:159], v[96:99]
	v_mfma_f32_16x16x32_bf16 v[92:95], v[140:143], v[132:135], v[92:95]
	v_mfma_f32_16x16x32_bf16 v[76:79], v[140:143], v[148:151], v[76:79]
	v_mfma_f32_16x16x32_bf16 v[88:91], v[144:147], v[132:135], v[88:91]
	v_mfma_f32_16x16x32_bf16 v[72:75], v[144:147], v[148:151], v[72:75]
	v_mfma_f32_16x16x32_bf16 v[84:87], v[136:139], v[132:135], v[84:87]
	v_mfma_f32_16x16x32_bf16 v[68:71], v[136:139], v[148:151], v[68:71]
	v_mfma_f32_16x16x32_bf16 v[80:83], v[128:131], v[132:135], v[80:83]
	v_mfma_f32_16x16x32_bf16 v[64:67], v[128:131], v[148:151], v[64:67]
	ds_read_b128 v[152:155], v191 offset:8192
	ds_read_b128 v[156:159], v191 offset:10240
	ds_read_b128 v[148:151], v191 offset:12288
	ds_read_b128 v[132:135], v191 offset:14336
	s_cbranch_vccnz .LBB0_580
	s_branch .LBB0_580

; #define MFMA32(a, b, c) __builtin_amdgcn_mfma_f32_32x32x16_bf16((a), (b), (c), 0, 0, 0)
; #define RAW_BARRIER() do { asm volatile("s_waitcnt lgkmcnt(0)" ::: "memory"); __builtin_amdgcn_s_barrier(); } while (0)
; template <int AMODE, bool SWAP, int MI>
; DI void mainloop_dma(f32x16 (&acc)[MI][2], const TD& c, const TD& n, bool hasn, bool primed, int& s, int tid) {
;     ...
;     for (int kt = 0; kt < nk; ++kt) {
;         int ns, nkt;
;         if (MI == 2) {
;             if (kt + 1 < nk && kt > 0) asm volatile("s_waitcnt vmcnt(6)" ::: "memory"); else asm volatile("s_waitcnt vmcnt(0)" ::: "memory");
;             RAW_BARRIER();
;             ns = s >= 1 ? s - 1 : 2; nkt = kt + 2;
;         } else {
;             asm volatile("s_waitcnt vmcnt(0)" ::: "memory");
;             RAW_BARRIER();
;             ns = s ^ 1; nkt = kt + 1;
;         }
;         const bool doload = nkt < nk;
;         const char* sb = smem + s * C::STAGE;
; #pragma unroll
;         for (int ks = 0; ks < 4; ++ks) {
;             const int co = (lk ^ (2 * ks)) << 4;
;             bf16x8 fa[MI], fb[2];
; #pragma unroll
;             for (int mi = 0; mi < MI; ++mi) fa[mi] = *(const bf16x8*)(sb + a_off + mi * 4096 + co);
;             fb[0] = *(const bf16x8*)(sb + b_off + co); fb[1] = *(const bf16x8*)(sb + b_off + 4096 + co);
;             asm volatile("" ::: "memory");
;             if (doload) {
;                 constexpr int P0[5] = {0, (NP + 3) / 4, (NP + 3) / 4 + (NP + 2) / 4, (NP + 3) / 4 + (NP + 2) / 4 + (NP + 1) / 4, NP};
; #pragma unroll
;                 for (int i = P0[ks]; i < P0[ks + 1]; ++i) piece(c, ao, bo, nkt, ns, i);
;             }
;             asm volatile("" ::: "memory");
; #pragma unroll
;             for (int mi = 0; mi < MI; ++mi)
; #pragma unroll
;                 for (int ni = 0; ni < 2; ++ni) {
;                     if (!SWAP) acc[mi][ni] = MFMA32(fa[mi], fb[ni], acc[mi][ni]);
;                     else acc[mi][ni] = MFMA32(fb[ni], fa[mi], acc[mi][ni]);
;                 }
;         }
.LBB0_789:
	s_cmp_lt_u32 s21, s48
	s_cselect_b64 s[40:41], -1, 0
	s_lshl_b32 s0, s28, 16
	s_add_i32 s1, s0, 16
	v_add3_u32 v170, s1, v224, v223
	s_waitcnt vmcnt(0)
	v_add_u32_e32 v128, v170, v233
	s_waitcnt lgkmcnt(0)
	s_barrier
	v_add3_u32 v169, s1, v225, v223
	ds_read_b128 v[148:151], v128
	ds_read_b128 v[144:147], v128 offset:4096
	ds_read_b128 v[132:135], v128 offset:8192
	ds_read_b128 v[128:131], v128 offset:12288
	v_add_u32_e32 v140, v169, v233
	ds_read_b128 v[136:139], v140 offset:32768
	ds_read_b128 v[140:143], v140 offset:36864
	s_xor_b32 s0, s0, 0x10000
	s_cmp_ge_u32 s21, s48
	v_add_u32_e32 v168, s0, v232
	s_cbranch_scc1 .LBB0_791
	v_lshl_add_u64 v[172:173], v[152:153], 0, s[38:39]
	v_readfirstlane_b32 s0, v168
	s_mov_b32 m0, s0
	s_nop 0
	global_load_lds_dwordx4 v[172:173], off
	v_add_u32_e32 v174, 0x400, v168
	v_lshl_add_u64 v[172:173], v[154:155], 0, s[38:39]
	v_readfirstlane_b32 s0, v174
	s_mov_b32 m0, s0
	s_nop 0
	global_load_lds_dwordx4 v[172:173], off
	v_add_u32_e32 v174, 0x800, v168
	v_lshl_add_u64 v[172:173], v[156:157], 0, s[38:39]
	v_readfirstlane_b32 s0, v174
	s_mov_b32 m0, s0
	s_nop 0
	global_load_lds_dwordx4 v[172:173], off
	v_add_u32_e32 v174, 0xc00, v168
	v_lshl_add_u64 v[172:173], v[158:159], 0, s[38:39]
	v_readfirstlane_b32 s0, v174
	s_mov_b32 m0, s0
	s_nop 0
	global_load_lds_dwordx4 v[172:173], off
.LBB0_791:
	s_waitcnt lgkmcnt(0)
	v_mfma_f32_32x32x16_bf16 v[112:127], v[136:139], v[148:151], v[112:127]
	v_cndmask_b32_e64 v171, 0, 1, s[40:41]
	v_cmp_ne_u32_e64 s[0:1], 1, v171
	s_andn2_b64 vcc, exec, s[40:41]
	v_mfma_f32_32x32x16_bf16 v[96:111], v[140:143], v[148:151], v[96:111]
	v_add_u32_e32 v148, v169, v234
	v_mfma_f32_32x32x16_bf16 v[80:95], v[136:139], v[144:147], v[80:95]
	v_mfma_f32_32x32x16_bf16 v[64:79], v[140:143], v[144:147], v[64:79]
	v_mfma_f32_32x32x16_bf16 v[48:63], v[136:139], v[132:135], v[48:63]
	v_mfma_f32_32x32x16_bf16 v[32:47], v[140:143], v[132:135], v[32:47]
	v_mfma_f32_32x32x16_bf16 v[16:31], v[136:139], v[128:131], v[16:31]
	v_add_u32_e32 v136, v170, v234
	v_mfma_f32_32x32x16_bf16 v[0:15], v[140:143], v[128:131], v[0:15]
	ds_read_b128 v[140:143], v136
	ds_read_b128 v[128:131], v136 offset:4096
	ds_read_b128 v[132:135], v136 offset:8192
	ds_read_b128 v[136:139], v136 offset:12288
	ds_read_b128 v[144:147], v148 offset:32768
	ds_read_b128 v[148:151], v148 offset:36864
	s_cbranch_vccnz .LBB0_793
	v_add_u32_e32 v174, 0x8000, v168
	v_lshl_add_u64 v[172:173], v[160:161], 0, s[38:39]
	v_readfirstlane_b32 s40, v174
	s_mov_b32 m0, s40
	s_nop 0
	global_load_lds_dwordx4 v[172:173], off
	v_add_u32_e32 v174, 0x8400, v168
	v_lshl_add_u64 v[172:173], v[162:163], 0, s[38:39]
	v_readfirstlane_b32 s40, v174
	s_mov_b32 m0, s40
	s_nop 0
	global_load_lds_dwordx4 v[172:173], off
	v_add_u32_e32 v174, 0x8800, v168
	v_lshl_add_u64 v[172:173], v[164:165], 0, s[38:39]
	v_readfirstlane_b32 s40, v174
	s_mov_b32 m0, s40
	s_nop 0
	global_load_lds_dwordx4 v[172:173], off
	v_add_u32_e32 v174, 0x8c00, v168
	v_lshl_add_u64 v[172:173], v[166:167], 0, s[38:39]
	v_readfirstlane_b32 s40, v174
	s_mov_b32 m0, s40
	s_nop 0
	global_load_lds_dwordx4 v[172:173], off

; #define MFMA32(a, b, c) __builtin_amdgcn_mfma_f32_32x32x16_bf16((a), (b), (c), 0, 0, 0)
; template <int AMODE, bool SWAP, int MI>
; DI void mainloop_dma(f32x16 (&acc)[MI][2], const TD& c, const TD& n, bool hasn, bool primed, int& s, int tid) {
;     ...
; #pragma unroll
;         for (int ks = 0; ks < 4; ++ks) {
;             const int co = (lk ^ (2 * ks)) << 4;
;             bf16x8 fa[MI], fb[2];
; #pragma unroll
;             for (int mi = 0; mi < MI; ++mi) fa[mi] = *(const bf16x8*)(sb + a_off + mi * 4096 + co);
;             fb[0] = *(const bf16x8*)(sb + b_off + co); fb[1] = *(const bf16x8*)(sb + b_off + 4096 + co);
;             asm volatile("" ::: "memory");
;             if (doload) {
;                 constexpr int P0[5] = {0, (NP + 3) / 4, (NP + 3) / 4 + (NP + 2) / 4, (NP + 3) / 4 + (NP + 2) / 4 + (NP + 1) / 4, NP};
; #pragma unroll
;                 for (int i = P0[ks]; i < P0[ks + 1]; ++i) piece(c, ao, bo, nkt, ns, i);
;             }
;             asm volatile("" ::: "memory");
; #pragma unroll
;             for (int mi = 0; mi < MI; ++mi)
; #pragma unroll
;                 for (int ni = 0; ni < 2; ++ni) {
;                     if (!SWAP) acc[mi][ni] = MFMA32(fa[mi], fb[ni], acc[mi][ni]);
;                     else acc[mi][ni] = MFMA32(fb[ni], fa[mi], acc[mi][ni]);
;                 }
;         }
.LBB0_795:
	s_waitcnt lgkmcnt(0)
	v_mfma_f32_32x32x16_bf16 v[112:127], v[136:139], v[148:151], v[112:127]
	s_and_b64 vcc, exec, s[0:1]
	v_mfma_f32_32x32x16_bf16 v[96:111], v[140:143], v[148:151], v[96:111]
	v_mfma_f32_32x32x16_bf16 v[80:95], v[136:139], v[144:147], v[80:95]
	v_mfma_f32_32x32x16_bf16 v[64:79], v[140:143], v[144:147], v[64:79]
	v_mfma_f32_32x32x16_bf16 v[48:63], v[136:139], v[132:135], v[48:63]
	v_mfma_f32_32x32x16_bf16 v[32:47], v[140:143], v[132:135], v[32:47]
	v_add_u32_e32 v132, v169, v236
	v_mfma_f32_32x32x16_bf16 v[16:31], v[136:139], v[128:131], v[16:31]
	v_mfma_f32_32x32x16_bf16 v[0:15], v[140:143], v[128:131], v[0:15]
	v_add_u32_e32 v128, v170, v236
	ds_read_b128 v[148:151], v128
	ds_read_b128 v[144:147], v128 offset:4096
	ds_read_b128 v[136:139], v128 offset:8192
	ds_read_b128 v[128:131], v128 offset:12288
	ds_read_b128 v[140:143], v132 offset:32768
	ds_read_b128 v[132:135], v132 offset:36864
	s_cbranch_vccnz .LBB0_788
	s_branch .LBB0_788

; #define MFMA16(a, b, c) __builtin_amdgcn_mfma_f32_16x16x32_bf16((a), (b), (c), 0, 0, 0)
; #define RAW_BARRIER() do { asm volatile("s_waitcnt lgkmcnt(0)" ::: "memory"); __builtin_amdgcn_s_barrier(); } while (0)
; template <int AMODE, bool SWAPO = true>
; DI void mainloop_dma16(f32x4 (&acc)[4][2][2][2], const TD& c, const TD& n, bool hasn, bool primed, int& s, int tid) {
;     ...
;     for (int kt = 0; kt < nk; ++kt) {
;         asm volatile("s_waitcnt vmcnt(0)" ::: "memory");
;         RAW_BARRIER();
;         const int ns = s ^ 1, nkt = kt + 1;
;         const bool doload = nkt < nk;
;         const char* sb = smem + s * C::STAGE;
; #pragma unroll
;         for (int k2 = 0; k2 < 2; ++k2) {
;             const int co = ((4 * k2 + q) ^ key) << 4;
;             bf16x8 fw[2][2];
; #pragma unroll
;             for (int ni = 0; ni < 2; ++ni)
; #pragma unroll
;                 for (int rh = 0; rh < 2; ++rh) fw[ni][rh] = *(const bf16x8*)(sb + b_off + (ni * 32 + rh * 16) * 128 + co);
; #pragma unroll
;             for (int mh = 0; mh < 2; ++mh) {
;                 bf16x8 fx[2][2];
; #pragma unroll
;                 for (int m2 = 0; m2 < 2; ++m2)
; #pragma unroll
;                     for (int ch = 0; ch < 2; ++ch) fx[m2][ch] = *(const bf16x8*)(sb + a_off + ((2 * mh + m2) * 32 + ch * 16) * 128 + co);
;                 asm volatile("" ::: "memory");
;                 if (doload) { const int p0 = (2 * k2 + mh) * 2; piece(c, ao, bo, nkt, ns, p0); piece(c, ao, bo, nkt, ns, p0 + 1); }
;                 asm volatile("" ::: "memory");
; #pragma unroll
;                 for (int m2 = 0; m2 < 2; ++m2)
; #pragma unroll
;                     for (int ni = 0; ni < 2; ++ni)
; #pragma unroll
;                         for (int rh = 0; rh < 2; ++rh)
; #pragma unroll
;                             for (int ch = 0; ch < 2; ++ch)
;                                 acc[2 * mh + m2][ni][rh][ch] = SWAPO ? MFMA16(fw[ni][rh], fx[m2][ch], acc[2 * mh + m2][ni][rh][ch]) : MFMA16(fx[m2][ch], fw[ni][rh], acc[2 * mh + m2][ni][rh][ch]);
;             }
.LBB0_1743:
	s_cmp_lt_u32 s28, 43
	s_cselect_b64 s[18:19], -1, 0
	s_lshl_b32 s0, s20, 16
	s_add_i32 s1, s0, 16
	v_add3_u32 v223, s1, v197, v195
	v_add3_u32 v222, s1, v196, v195
	s_waitcnt vmcnt(0)
	v_add_u32_e32 v96, v223, v205
	v_add_u32_e32 v224, v222, v205
	s_waitcnt lgkmcnt(0)
	s_barrier
	ds_read_b128 v[108:111], v96 offset:32768
	ds_read_b128 v[104:107], v96 offset:34816
	ds_read_b128 v[100:103], v96 offset:36864
	ds_read_b128 v[96:99], v96 offset:38912
	ds_read_b128 v[168:171], v224
	ds_read_b128 v[172:175], v224 offset:2048
	ds_read_b128 v[160:163], v224 offset:4096
	ds_read_b128 v[164:167], v224 offset:6144
	s_xor_b32 s0, s0, 0x10000
	s_cmp_gt_u32 s28, 42
	v_add_u32_e32 v176, s0, v204
	s_cbranch_scc1 .LBB0_1745
	v_lshl_add_u64 v[112:113], v[178:179], 0, s[8:9]
	v_readfirstlane_b32 s0, v176
	s_mov_b32 m0, s0
	s_nop 0
	global_load_lds_dwordx4 v[112:113], off
	v_add_u32_e32 v114, 0x400, v176
	v_lshl_add_u64 v[112:113], v[180:181], 0, s[8:9]
	v_readfirstlane_b32 s0, v114
	s_mov_b32 m0, s0
	s_nop 0
	global_load_lds_dwordx4 v[112:113], off
	v_add_u32_e32 v114, 0x800, v176
	v_lshl_add_u64 v[112:113], v[182:183], 0, s[8:9]
	v_readfirstlane_b32 s0, v114
	s_mov_b32 m0, s0
	s_nop 0
	global_load_lds_dwordx4 v[112:113], off
	v_add_u32_e32 v114, 0xc00, v176
	v_lshl_add_u64 v[112:113], v[184:185], 0, s[8:9]
	v_readfirstlane_b32 s0, v114
	s_mov_b32 m0, s0
	s_nop 0
	global_load_lds_dwordx4 v[112:113], off
.LBB0_1745:
	s_waitcnt lgkmcnt(0)
	v_mfma_f32_16x16x32_bf16 v[112:115], v[108:111], v[168:171], v[156:159]
	s_andn2_b64 vcc, exec, s[18:19]
	v_mfma_f32_16x16x32_bf16 v[116:119], v[108:111], v[172:175], v[140:143]
	v_mfma_f32_16x16x32_bf16 v[120:123], v[104:107], v[168:171], v[152:155]
	v_mfma_f32_16x16x32_bf16 v[124:127], v[104:107], v[172:175], v[136:139]
	s_nop 1
	ds_read_b128 v[152:155], v224 offset:8192
	ds_read_b128 v[156:159], v224 offset:10240
	ds_read_b128 v[136:139], v224 offset:12288
	ds_read_b128 v[140:143], v224 offset:14336
	v_mfma_f32_16x16x32_bf16 v[148:151], v[100:103], v[168:171], v[148:151]
	v_mfma_f32_16x16x32_bf16 v[132:135], v[100:103], v[172:175], v[132:135]
	v_mfma_f32_16x16x32_bf16 v[144:147], v[96:99], v[168:171], v[144:147]
	v_mfma_f32_16x16x32_bf16 v[128:131], v[96:99], v[172:175], v[128:131]
	v_mfma_f32_16x16x32_bf16 v[92:95], v[108:111], v[160:163], v[92:95]
	v_mfma_f32_16x16x32_bf16 v[76:79], v[108:111], v[164:167], v[76:79]
	v_mfma_f32_16x16x32_bf16 v[88:91], v[104:107], v[160:163], v[88:91]
	v_mfma_f32_16x16x32_bf16 v[72:75], v[104:107], v[164:167], v[72:75]
	v_mfma_f32_16x16x32_bf16 v[84:87], v[100:103], v[160:163], v[84:87]
	v_mfma_f32_16x16x32_bf16 v[68:71], v[100:103], v[164:167], v[68:71]
	v_mfma_f32_16x16x32_bf16 v[80:83], v[96:99], v[160:163], v[80:83]
	v_cndmask_b32_e64 v160, 0, 1, s[18:19]
	v_cmp_ne_u32_e64 s[0:1], 1, v160
	v_mfma_f32_16x16x32_bf16 v[64:67], v[96:99], v[164:167], v[64:67]
	s_cbranch_vccnz .LBB0_1747
	v_add_u32_e32 v162, 0x8000, v176
	v_lshl_add_u64 v[160:161], v[186:187], 0, s[8:9]
	v_readfirstlane_b32 s18, v162
	s_mov_b32 m0, s18
	s_nop 0
	global_load_lds_dwordx4 v[160:161], off
	v_add_u32_e32 v162, 0x8400, v176
	v_lshl_add_u64 v[160:161], v[188:189], 0, s[8:9]
	v_readfirstlane_b32 s18, v162
	s_mov_b32 m0, s18
	s_nop 0
	global_load_lds_dwordx4 v[160:161], off
	v_add_u32_e32 v162, 0x8800, v176
	v_lshl_add_u64 v[160:161], v[190:191], 0, s[8:9]
	v_readfirstlane_b32 s18, v162
	s_mov_b32 m0, s18
	s_nop 0
	global_load_lds_dwordx4 v[160:161], off
	v_add_u32_e32 v162, 0x8c00, v176
	v_lshl_add_u64 v[160:161], v[192:193], 0, s[8:9]
	v_readfirstlane_b32 s18, v162
	s_mov_b32 m0, s18
	s_nop 0
	global_load_lds_dwordx4 v[160:161], off

; #define MFMA16(a, b, c) __builtin_amdgcn_mfma_f32_16x16x32_bf16((a), (b), (c), 0, 0, 0)
; template <int AMODE, bool SWAPO = true>
; DI void mainloop_dma16(f32x4 (&acc)[4][2][2][2], const TD& c, const TD& n, bool hasn, bool primed, int& s, int tid) {
;     ...
; #pragma unroll
;         for (int k2 = 0; k2 < 2; ++k2) {
;             const int co = ((4 * k2 + q) ^ key) << 4;
;             bf16x8 fw[2][2];
; #pragma unroll
;             for (int ni = 0; ni < 2; ++ni)
; #pragma unroll
;                 for (int rh = 0; rh < 2; ++rh) fw[ni][rh] = *(const bf16x8*)(sb + b_off + (ni * 32 + rh * 16) * 128 + co);
; #pragma unroll
;             for (int mh = 0; mh < 2; ++mh) {
;                 bf16x8 fx[2][2];
; #pragma unroll
;                 for (int m2 = 0; m2 < 2; ++m2)
; #pragma unroll
;                     for (int ch = 0; ch < 2; ++ch) fx[m2][ch] = *(const bf16x8*)(sb + a_off + ((2 * mh + m2) * 32 + ch * 16) * 128 + co);
;                 asm volatile("" ::: "memory");
;                 if (doload) { const int p0 = (2 * k2 + mh) * 2; piece(c, ao, bo, nkt, ns, p0); piece(c, ao, bo, nkt, ns, p0 + 1); }
;                 asm volatile("" ::: "memory");
; #pragma unroll
;                 for (int m2 = 0; m2 < 2; ++m2)
; #pragma unroll
;                     for (int ni = 0; ni < 2; ++ni)
; #pragma unroll
;                         for (int rh = 0; rh < 2; ++rh)
; #pragma unroll
;                             for (int ch = 0; ch < 2; ++ch)
;                                 acc[2 * mh + m2][ni][rh][ch] = SWAPO ? MFMA16(fw[ni][rh], fx[m2][ch], acc[2 * mh + m2][ni][rh][ch]) : MFMA16(fx[m2][ch], fw[ni][rh], acc[2 * mh + m2][ni][rh][ch]);
;             }
.LBB0_1749:
	s_waitcnt lgkmcnt(0)
	v_mfma_f32_16x16x32_bf16 v[156:159], v[108:111], v[168:171], v[112:115]
	s_and_b64 vcc, exec, s[0:1]
	v_mfma_f32_16x16x32_bf16 v[140:143], v[108:111], v[172:175], v[116:119]
	v_mfma_f32_16x16x32_bf16 v[152:155], v[160:163], v[168:171], v[120:123]
	v_mfma_f32_16x16x32_bf16 v[92:95], v[108:111], v[100:103], v[92:95]
	v_mfma_f32_16x16x32_bf16 v[88:91], v[160:163], v[100:103], v[88:91]
	v_mfma_f32_16x16x32_bf16 v[84:87], v[104:107], v[100:103], v[84:87]
	v_mfma_f32_16x16x32_bf16 v[80:83], v[96:99], v[100:103], v[80:83]
	ds_read_b128 v[116:119], v222 offset:8192
	ds_read_b128 v[120:123], v222 offset:10240
	ds_read_b128 v[112:115], v222 offset:12288
	ds_read_b128 v[100:103], v222 offset:14336
	v_mfma_f32_16x16x32_bf16 v[136:139], v[160:163], v[172:175], v[124:127]
	v_mfma_f32_16x16x32_bf16 v[148:151], v[104:107], v[168:171], v[148:151]
	v_mfma_f32_16x16x32_bf16 v[132:135], v[104:107], v[172:175], v[132:135]
	v_mfma_f32_16x16x32_bf16 v[144:147], v[96:99], v[168:171], v[144:147]
	v_mfma_f32_16x16x32_bf16 v[128:131], v[96:99], v[172:175], v[128:131]
	v_mfma_f32_16x16x32_bf16 v[76:79], v[108:111], v[164:167], v[76:79]
	v_mfma_f32_16x16x32_bf16 v[72:75], v[160:163], v[164:167], v[72:75]
	v_mfma_f32_16x16x32_bf16 v[68:71], v[104:107], v[164:167], v[68:71]
	v_mfma_f32_16x16x32_bf16 v[64:67], v[96:99], v[164:167], v[64:67]
	s_cbranch_vccnz .LBB0_1742
	s_branch .LBB0_1742
